# GEMM main loop head aligned to a 64-byte boundary (code placement only), on top of v74
# speedup vs baseline: 1.0019x; 1.0015x over previous
.LBB0_2001:
	s_add_u32 s11, s24, 0x100
	s_addc_u32 s71, s25, 0
	s_add_u32 s2, s72, 0x80
	v_mov_b32_e32 v2, 0
	s_addc_u32 s3, s73, 0
	v_mov_b32_e32 v3, v2
	v_mov_b32_e32 v4, v2
	v_mov_b32_e32 v5, v2
	v_mov_b32_e32 v6, v2
	v_mov_b32_e32 v7, v2
	v_mov_b32_e32 v8, v2
	v_mov_b32_e32 v9, v2
	v_mov_b32_e32 v18, v2
	v_mov_b32_e32 v19, v2
	v_mov_b32_e32 v20, v2
	v_mov_b32_e32 v21, v2
	v_mov_b32_e32 v22, v2
	v_mov_b32_e32 v23, v2
	v_mov_b32_e32 v24, v2
	v_mov_b32_e32 v25, v2
	v_mov_b32_e32 v34, v2
	v_mov_b32_e32 v35, v2
	v_mov_b32_e32 v36, v2
	v_mov_b32_e32 v37, v2
	v_mov_b32_e32 v46, v2
	v_mov_b32_e32 v47, v2
	v_mov_b32_e32 v48, v2
	v_mov_b32_e32 v49, v2
	v_mov_b32_e32 v58, v2
	v_mov_b32_e32 v59, v2
	v_mov_b32_e32 v60, v2
	v_mov_b32_e32 v61, v2
	v_mov_b32_e32 v62, v2
	v_mov_b32_e32 v63, v2
	v_mov_b32_e32 v64, v2
	v_mov_b32_e32 v65, v2
	v_mov_b32_e32 v10, v2
	v_mov_b32_e32 v11, v2
	v_mov_b32_e32 v12, v2
	v_mov_b32_e32 v13, v2
	v_mov_b32_e32 v14, v2
	v_mov_b32_e32 v15, v2
	v_mov_b32_e32 v16, v2
	v_mov_b32_e32 v17, v2
	v_mov_b32_e32 v26, v2
	v_mov_b32_e32 v27, v2
	v_mov_b32_e32 v28, v2
	v_mov_b32_e32 v29, v2
	v_mov_b32_e32 v30, v2
	v_mov_b32_e32 v31, v2
	v_mov_b32_e32 v32, v2
	v_mov_b32_e32 v33, v2
	v_mov_b32_e32 v38, v2
	v_mov_b32_e32 v39, v2
	v_mov_b32_e32 v40, v2
	v_mov_b32_e32 v41, v2
	v_mov_b32_e32 v42, v2
	v_mov_b32_e32 v43, v2
	v_mov_b32_e32 v44, v2
	v_mov_b32_e32 v45, v2
	v_mov_b32_e32 v50, v2
	v_mov_b32_e32 v51, v2
	v_mov_b32_e32 v52, v2
	v_mov_b32_e32 v53, v2
	v_mov_b32_e32 v54, v2
	v_mov_b32_e32 v55, v2
	v_mov_b32_e32 v56, v2
	v_mov_b32_e32 v57, v2
	v_mov_b32_e32 v74, v2
	v_mov_b32_e32 v75, v2
	v_mov_b32_e32 v76, v2
	v_mov_b32_e32 v77, v2
	v_mov_b32_e32 v78, v2
	v_mov_b32_e32 v79, v2
	v_mov_b32_e32 v80, v2
	v_mov_b32_e32 v81, v2
	v_mov_b32_e32 v90, v2
	v_mov_b32_e32 v91, v2
	v_mov_b32_e32 v92, v2
	v_mov_b32_e32 v93, v2
	v_mov_b32_e32 v94, v2
	v_mov_b32_e32 v95, v2
	v_mov_b32_e32 v96, v2
	v_mov_b32_e32 v97, v2
	v_mov_b32_e32 v106, v2
	v_mov_b32_e32 v107, v2
	v_mov_b32_e32 v108, v2
	v_mov_b32_e32 v109, v2
	v_mov_b32_e32 v110, v2
	v_mov_b32_e32 v111, v2
	v_mov_b32_e32 v112, v2
	v_mov_b32_e32 v113, v2
	v_mov_b32_e32 v126, v2
	v_mov_b32_e32 v127, v2
	v_mov_b32_e32 v128, v2
	v_mov_b32_e32 v129, v2
	v_mov_b32_e32 v114, v2
	v_mov_b32_e32 v115, v2
	v_mov_b32_e32 v116, v2
	v_mov_b32_e32 v117, v2
	v_mov_b32_e32 v66, v2
	v_mov_b32_e32 v67, v2
	v_mov_b32_e32 v68, v2
	v_mov_b32_e32 v69, v2
	v_mov_b32_e32 v70, v2
	v_mov_b32_e32 v71, v2
	v_mov_b32_e32 v72, v2
	v_mov_b32_e32 v73, v2
	v_mov_b32_e32 v82, v2
	v_mov_b32_e32 v83, v2
	v_mov_b32_e32 v84, v2
	v_mov_b32_e32 v85, v2
	v_mov_b32_e32 v86, v2
	v_mov_b32_e32 v87, v2
	v_mov_b32_e32 v88, v2
	v_mov_b32_e32 v89, v2
	v_mov_b32_e32 v98, v2
	v_mov_b32_e32 v99, v2
	v_mov_b32_e32 v100, v2
	v_mov_b32_e32 v101, v2
	v_mov_b32_e32 v102, v2
	v_mov_b32_e32 v103, v2
	v_mov_b32_e32 v104, v2
	v_mov_b32_e32 v105, v2
	v_mov_b32_e32 v118, v2
	v_mov_b32_e32 v119, v2
	v_mov_b32_e32 v120, v2
	v_mov_b32_e32 v121, v2
	v_mov_b32_e32 v122, v2
	v_mov_b32_e32 v123, v2
	v_mov_b32_e32 v124, v2
	v_mov_b32_e32 v125, v2
	.p2align 6
